# A-loop: K/V LDS-DMA addressing moved to SGPR bases + 8 precomputed 32-bit lane offsets (no per-step VALU address math, no readfirstlane); hazard pad kept
# speedup vs baseline: 1.0236x; 1.0145x over previous
; DI void pv_frag_step(f32x16& s0, f32x16& s1, const u16* Vs, f32x16& o0, f32x16& o1, f32x4& ls, bf16x8 ones, int rs, const int (&lo)[4]) {
; #pragma unroll
;   for (int i = 0; i < 16; ++i) { s0[i] = ex2(s0[i]); s1[i] = ex2(s1[i]); }
; #pragma unroll
;   for (int kk = 0; kk < 4; ++kk) {
;     const int s = kk & 1;
;     unsigned u0, u1, u2, u3;
;     if (kk < 2) {
;       u0 = pk2(s0[8 * s], s0[8 * s + 1]); u1 = pk2(s0[8 * s + 2], s0[8 * s + 3]);
;       u2 = pk2(s0[8 * s + 4], s0[8 * s + 5]); u3 = pk2(s0[8 * s + 6], s0[8 * s + 7]);
;     } else {
;       u0 = pk2(s1[8 * s], s1[8 * s + 1]); u1 = pk2(s1[8 * s + 2], s1[8 * s + 3]);
;       u2 = pk2(s1[8 * s + 4], s1[8 * s + 5]); u3 = pk2(s1[8 * s + 6], s1[8 * s + 7]);
;     }
;     u32x4 uu = {u0, u1, u2, u3};
;     bf16x8 pf = __builtin_bit_cast(bf16x8, uu);
;     bf16x8 v0 = ldsv(Vs + lo[kk]);
;     bf16x8 v1 = ldsv(Vs + 32 * rs + lo[kk]);
;     o0 = mfma(v0, pf, o0);
;     o1 = mfma(v1, pf, o1);
;     ls = mfma16(ones, pf, ls);
;   }
; DI void attn_item_A(const Params& p, int layer, int b, int head, int qb, u16* sm, float lam, float lam_init, int wv) {
;     ...
;   auto dma_tile = [&](int T, int c) {
;     const int k0 = 64 * T;
;     u16* Kd = Kb0 + c * (2 * 64 * 64) + wp * (8 * 64);
; #pragma unroll
;     for (int i = 0; i < 4; ++i) {
;       __builtin_amdgcn_global_load_lds((const unsigned*)(kg + (size_t)(k0 + row0 + 16 * i) * DIN), (unsigned*)(Kd + i * 16 * 64), 16, 0, 0);
;       __builtin_amdgcn_global_load_lds((const unsigned*)(vg + (size_t)(row0 + 16 * i) * SEQ + k0), (unsigned*)(Kd + 64 * 64 + i * 16 * 64), 16, 0, 0);
;     }
;   };
;   if (v0) dma_tile(T0, 0);
;   asm volatile("" :: "v"(qf[0]), "v"(qf[1]), "v"(qf[2]), "v"(qf[3]));
;   asm volatile("s_waitcnt vmcnt(0)" ::: "memory");
;   __syncthreads();
;   for (int j = 0; j < npairs; ++j) {
;     if (j + 1 < npairs) dma_tile(T0 - 2 * (j + 1), (j + 1) & 1);
;     if (j > 0 || v0) {
;       const int T = T0 - 2 * j;
;       const u16* Ks = Kb0 + (j & 1) * (2 * 64 * 64);
;       const u16* Vs = Ks + 64 * 64;
;       const int k0 = 64 * T;
;       const bool need_mask = (T == qb);
;       const int dl = qpos - k0 - 4 * h;
;       diff_softmax_pv(qf, Ks, Vs, m0, ls0, ls1, ones, o, sl2, dl, need_mask, !started, r, h, 64, lo);
;       m1 = m0;
;       started = true;
;     }
;     asm volatile("s_waitcnt vmcnt(0)" ::: "memory");
;     __syncthreads();
;   }
.LBB0_276:
	s_or_b64 exec, exec, s[18:19]
	s_waitcnt vmcnt(0)
	v_and_b32_e32 v205, 60, v125
	s_waitcnt vmcnt(0) lgkmcnt(0)
	s_barrier
	s_and_saveexec_b64 s[18:19], vcc
	s_cbranch_execz .LBB0_292
	v_add_u32_e32 v66, v120, v171
	v_sub_u32_e32 v66, v66, v124
	v_lshlrev_b32_e32 v67, 6, v118
	v_sub_u32_e32 v66, v66, v67
	v_lshlrev_b32_e32 v206, 6, v173
	v_lshlrev_b32_e32 v67, 6, v119
	v_sub_u32_e32 v66, v66, v206
	v_and_b32_e32 v67, 0xffffff80, v67
	v_sub_u32_e32 v66, v66, v67
	v_add_u32_e32 v207, 0x2040, v66
	v_add_u32_e32 v66, v118, v173
	s_movk_i32 s2, 0xff7f
	v_add3_u32 v208, v66, v123, s2
	v_or_b32_e32 v66, v121, v67
	v_cmp_gt_u32_e64 s[36:37], 16, v171
	v_add_u32_e32 v209, v66, v122
	v_add_u32_e32 v210, 0xffffff00, v67
	v_add_u32_e32 v72, v206, v209
	v_add_u32_e32 v68, 0xffffff00, v72
	v_mad_i64_i32 v[68:69], s[38:39], v68, s8, v[160:161]
	v_readlane_b32 s22, v250, 19
	v_add_u32_e32 v66, v206, v210
	v_ashrrev_i32_e32 v67, 31, v66
	v_lshl_add_u64 v[68:69], v[68:69], 0, s[68:69]
	v_lshlrev_b64 v[66:67], 1, v[66:67]
	v_or_b32_e32 v74, v121, v122
	v_subrev_u32_e32 v75, s22, v160
	v_lshl_add_u64 v[70:71], v[162:163], 0, v[66:67]
	v_mul_u32_u24_e32 v76, 0x1a00, v74
	v_lshlrev_b32_e32 v77, 14, v74
	v_add_u32_e32 v76, v76, v75
	v_add_u32_e32 v77, v77, v75
	v_sub_co_u32_e32 v68, vcc, v68, v76
	s_nop 1
	v_subbrev_co_u32_e32 v69, vcc, 0, v69, vcc
	v_sub_co_u32_e32 v70, vcc, v70, v77
	s_nop 1
	v_subbrev_co_u32_e32 v71, vcc, 0, v71, vcc
	v_mov_b32_e32 v160, v76
	v_readfirstlane_b32 s98, v68
	v_readfirstlane_b32 s99, v69
	v_readfirstlane_b32 s100, v70
	v_readfirstlane_b32 s101, v71
	v_readfirstlane_b32 s87, v177
	v_add_u32_e32 v161, 0x1a000, v76
	v_add_u32_e32 v162, 0x34000, v76
	v_add_u32_e32 v163, 0x4e000, v76
	v_mov_b32_e32 v164, v77
	v_add_u32_e32 v165, 0x40000, v77
	v_add_u32_e32 v166, 0x80000, v77
	v_add_u32_e32 v167, 0xc0000, v77
	s_movk_i32 s64, 0x2000
	s_mov_b32 s65, 0
	s_mov_b64 s[40:41], 0
	s_mov_b64 s[42:43], s[4:5]
	s_branch .LBB0_279
.LBB0_278:
	s_or_b64 exec, exec, s[2:3]
	s_nop 5
	v_exp_f32_e32 v66, v66
	v_exp_f32_e32 v67, v67
	v_exp_f32_e32 v68, v68
	v_exp_f32_e32 v69, v69
	v_exp_f32_e32 v70, v70
	v_exp_f32_e32 v71, v71
	v_exp_f32_e32 v72, v72
	v_exp_f32_e32 v73, v73
	v_cvt_pk_bf16_f32 v66, v66, v67
	v_cvt_pk_bf16_f32 v67, v68, v69
	v_cvt_pk_bf16_f32 v68, v70, v71
	v_cvt_pk_bf16_f32 v69, v72, v73
	v_exp_f32_e32 v74, v74
	v_exp_f32_e32 v75, v75
	v_mfma_f32_32x32x16_bf16 v[50:65], v[98:101], v[66:69], v[50:65]
	v_exp_f32_e32 v76, v76
	v_exp_f32_e32 v77, v77
	v_exp_f32_e32 v78, v78
	v_exp_f32_e32 v79, v79
	v_exp_f32_e32 v80, v80
	v_exp_f32_e32 v81, v81
	v_cvt_pk_bf16_f32 v70, v74, v75
	v_mfma_f32_32x32x16_bf16 v[18:33], v[102:105], v[66:69], v[18:33]
	v_cvt_pk_bf16_f32 v71, v76, v77
	v_cvt_pk_bf16_f32 v73, v80, v81
	v_cvt_pk_bf16_f32 v72, v78, v79
	v_exp_f32_e32 v82, v82
	v_exp_f32_e32 v83, v83
	v_exp_f32_e32 v84, v84
	v_exp_f32_e32 v85, v85
	v_mfma_f32_32x32x16_bf16 v[50:65], v[106:109], v[70:73], v[50:65]
	v_exp_f32_e32 v86, v86
	v_exp_f32_e32 v87, v87
	v_exp_f32_e32 v88, v88
	v_exp_f32_e32 v89, v89
	v_exp_f32_e32 v90, v90
	v_exp_f32_e32 v91, v91
	v_exp_f32_e32 v92, v92
	v_mfma_f32_32x32x16_bf16 v[18:33], v[110:113], v[70:73], v[18:33]
	v_exp_f32_e32 v93, v93
	v_exp_f32_e32 v94, v94
	v_exp_f32_e32 v95, v95
	v_exp_f32_e32 v96, v96
	v_exp_f32_e32 v97, v97
	s_waitcnt vmcnt(0)
	s_addk_i32 s64, 0x2000
	v_mfma_f32_16x16x32_bf16 v[66:69], v[146:149], v[66:69], v[154:157]
	v_cmp_eq_u32_e32 vcc, s65, v180
	v_add_u32_e32 v207, 0x80, v207
	v_add_u32_e32 v208, -2, v208
	v_mfma_f32_16x16x32_bf16 v[66:69], v[146:149], v[70:73], v[66:69]
	v_cvt_pk_bf16_f32 v70, v82, v83
	v_cvt_pk_bf16_f32 v71, v84, v85
	v_cvt_pk_bf16_f32 v73, v88, v89
	v_cvt_pk_bf16_f32 v72, v86, v87
	s_nop 1
	v_mfma_f32_32x32x16_bf16 v[50:65], v[114:117], v[70:73], v[50:65]
	s_or_b64 s[40:41], vcc, s[40:41]
	s_mov_b64 s[42:43], -1
	s_barrier
	v_mfma_f32_32x32x16_bf16 v[18:33], v[118:121], v[70:73], v[18:33]
	v_mfma_f32_16x16x32_bf16 v[66:69], v[146:149], v[70:73], v[66:69]
	v_cvt_pk_bf16_f32 v70, v90, v91
	v_cvt_pk_bf16_f32 v71, v92, v93
	v_cvt_pk_bf16_f32 v73, v96, v97
	v_cvt_pk_bf16_f32 v72, v94, v95
	s_nop 1
	v_mfma_f32_32x32x16_bf16 v[50:65], v[122:125], v[70:73], v[50:65]
	v_mfma_f32_32x32x16_bf16 v[18:33], v[126:129], v[70:73], v[18:33]
	v_mfma_f32_16x16x32_bf16 v[154:157], v[146:149], v[70:73], v[66:69]
	s_andn2_b64 exec, exec, s[40:41]
	s_cbranch_execz .LBB0_291
.LBB0_279:
	s_add_i32 s65, s65, 1
	v_cmp_lt_i32_e32 vcc, s65, v180
	s_and_saveexec_b64 s[2:3], vcc
	s_cbranch_execz .LBB0_281
	s_add_i32 s38, s64, 0x2000
	s_and_b32 s38, s38, 0x2000
	s_lshl_b32 s38, s38, 1
	s_add_i32 s38, s38, s87
	s_mov_b32 m0, s38
	s_add_i32 s22, s38, 0x2000
	global_load_lds_dwordx4 v160, s[98:99]
	s_mov_b32 m0, s22
	s_add_i32 s32, s38, 0x800
	global_load_lds_dwordx4 v164, s[100:101]
	s_mov_b32 m0, s32
	s_add_i32 s22, s38, 0x2800
	global_load_lds_dwordx4 v161, s[98:99]
	s_mov_b32 m0, s22
	s_add_i32 s32, s38, 0x1000
	global_load_lds_dwordx4 v165, s[100:101]
	s_mov_b32 m0, s32
	s_add_i32 s22, s38, 0x3000
	global_load_lds_dwordx4 v162, s[98:99]
	s_mov_b32 m0, s22
	s_add_i32 s32, s38, 0x1800
	global_load_lds_dwordx4 v166, s[100:101]
	s_mov_b32 m0, s32
	s_add_i32 s22, s38, 0x3800
	global_load_lds_dwordx4 v163, s[98:99]
	s_mov_b32 m0, s22
	s_add_u32 s98, s98, 0xfff30000
	s_addc_u32 s99, s99, -1
	global_load_lds_dwordx4 v167, s[100:101]
	s_sub_u32 s100, s100, 0x100
	s_subb_u32 s101, s101, 0

; __global__ void __launch_bounds__(256, 2) hymba_mega(Params p) {
;   cg::grid_group grid = cg::this_grid();
;   __shared__ __attribute__((aligned(16))) u16 sm[SMEM_U16];
;   __shared__ int s_item;
;   __shared__ int s_done[4];
;   const int wv = __builtin_amdgcn_readfirstlane((int)threadIdx.x >> 6);
	.amdhsa_kernel _Z10hymba_mega6Params
		.amdhsa_group_segment_fixed_size 73764
		.amdhsa_private_segment_fixed_size 0
		.amdhsa_kernarg_size 440
		.amdhsa_user_sgpr_count 2
		.amdhsa_user_sgpr_dispatch_ptr 0
		.amdhsa_user_sgpr_queue_ptr 0
		.amdhsa_user_sgpr_kernarg_segment_ptr 1
		.amdhsa_user_sgpr_dispatch_id 0
		.amdhsa_user_sgpr_kernarg_preload_length 0
		.amdhsa_user_sgpr_kernarg_preload_offset 0
		.amdhsa_user_sgpr_private_segment_size 0
		.amdhsa_uses_dynamic_stack 0
		.amdhsa_enable_private_segment 0
		.amdhsa_system_sgpr_workgroup_id_x 1
		.amdhsa_system_sgpr_workgroup_id_y 0
		.amdhsa_system_sgpr_workgroup_id_z 0
		.amdhsa_system_sgpr_workgroup_info 0
		.amdhsa_system_vgpr_workitem_id 2
		.amdhsa_next_free_vgpr 252
		.amdhsa_next_free_sgpr 102
		.amdhsa_accum_offset 252
		.amdhsa_reserve_vcc 1
		.amdhsa_float_round_mode_32 0
		.amdhsa_float_round_mode_16_64 0
		.amdhsa_float_denorm_mode_32 3
		.amdhsa_float_denorm_mode_16_64 3
		.amdhsa_dx10_clamp 1
		.amdhsa_ieee_mode 1
		.amdhsa_fp16_overflow 0
		.amdhsa_tg_split 0
		.amdhsa_exception_fp_ieee_invalid_op 0
		.amdhsa_exception_fp_denorm_src 0
		.amdhsa_exception_fp_ieee_div_zero 0
		.amdhsa_exception_fp_ieee_overflow 0
		.amdhsa_exception_fp_ieee_underflow 0
		.amdhsa_exception_fp_ieee_inexact 0
		.amdhsa_exception_int_div_zero 0
	.end_amdhsa_kernel

; __global__ void __launch_bounds__(256, 2) hymba_mega(Params p) {
;   cg::grid_group grid = cg::this_grid();
;   __shared__ __attribute__((aligned(16))) u16 sm[SMEM_U16];
;   __shared__ int s_item;
;   __shared__ int s_done[4];
;   const int wv = __builtin_amdgcn_readfirstlane((int)threadIdx.x >> 6);
amdhsa.kernels:
  - .agpr_count:     0
    .args:
      - .offset:         0
        .size:           184
        .value_kind:     by_value
      - .offset:         184
        .size:           4
        .value_kind:     hidden_block_count_x
      - .offset:         188
        .size:           4
        .value_kind:     hidden_block_count_y
      - .offset:         192
        .size:           4
        .value_kind:     hidden_block_count_z
      - .offset:         196
        .size:           2
        .value_kind:     hidden_group_size_x
      - .offset:         198
        .size:           2
        .value_kind:     hidden_group_size_y
      - .offset:         200
        .size:           2
        .value_kind:     hidden_group_size_z
      - .offset:         202
        .size:           2
        .value_kind:     hidden_remainder_x
      - .offset:         204
        .size:           2
        .value_kind:     hidden_remainder_y
      - .offset:         206
        .size:           2
        .value_kind:     hidden_remainder_z
      - .offset:         224
        .size:           8
        .value_kind:     hidden_global_offset_x
      - .offset:         232
        .size:           8
        .value_kind:     hidden_global_offset_y
      - .offset:         240
        .size:           8
        .value_kind:     hidden_global_offset_z
      - .offset:         248
        .size:           2
        .value_kind:     hidden_grid_dims
      - .offset:         272
        .size:           8
        .value_kind:     hidden_multigrid_sync_arg
    .group_segment_fixed_size: 73764
    .kernarg_segment_align: 8
    .kernarg_segment_size: 440
    .language:       OpenCL C
    .language_version:
      - 2
      - 0
    .max_flat_workgroup_size: 256
    .name:           _Z10hymba_mega6Params
    .private_segment_fixed_size: 0
    .sgpr_count:     108
    .sgpr_spill_count: 103
    .symbol:         _Z10hymba_mega6Params.kd
    .uniform_work_group_size: 1
    .uses_dynamic_stack: false
    .vgpr_count:     252
    .vgpr_spill_count: 0
    .wavefront_size: 64
